# phase 11: every other group of eight workgroups converts its ffn_w_in tiles before its LN1 rows (read-heavy and write-heavy streams side by side)
# speedup vs baseline: 1.0060x; 1.0060x over previous
.LBB0_1361:
	s_cmp_lt_i32 s68, 12
	s_cselect_b64 s[6:7], -1, 0
	s_and_b64 s[12:13], s[6:7], s[4:5]
	s_andn2_b64 vcc, exec, s[12:13]
	v_lshrrev_b32_e32 v206, 4, v1
	s_cbranch_vccnz .LBB0_1371
	s_load_dwordx8 s[4:11], s[0:1], 0xc0
	s_cmpk_lg_u32 s70, 0x100
	s_cbranch_scc1 .Lp11_ln
	s_bitcmp1_b32 s2, 3
	s_cbranch_scc1 .Lp11_conv
.Lp11_ln:
	v_and_b32_e32 v2, 60, v206
	v_lshl_add_u32 v18, s2, 5, v2
	s_movk_i32 s14, 0x4000
	v_cmp_gt_i32_e32 vcc, s14, v18
	s_and_saveexec_b64 s[14:15], vcc
	s_cbranch_execz .LBB0_1365
	v_mbcnt_lo_u32_b32 v3, -1, 0
	v_mbcnt_hi_u32_b32 v3, -1, v3
	v_and_b32_e32 v7, 64, v3
	v_add_u32_e32 v7, 64, v7
	v_xor_b32_e32 v8, 32, v3
	v_cmp_lt_i32_e32 vcc, v8, v7
	v_lshlrev_b32_e32 v2, 3, v1
	v_and_b32_e32 v2, 0x1f8, v2
	v_cndmask_b32_e32 v8, v3, v8, vcc
	v_lshlrev_b32_e32 v71, 2, v8
	v_xor_b32_e32 v8, 16, v3
	v_cmp_lt_i32_e32 vcc, v8, v7
	v_mov_b32_e32 v21, 0
	v_lshlrev_b32_e32 v20, 1, v2
	v_cndmask_b32_e32 v8, v3, v8, vcc
	v_lshlrev_b32_e32 v72, 2, v8
	v_xor_b32_e32 v8, 8, v3
	v_cmp_lt_i32_e32 vcc, v8, v7
	v_lshl_add_u64 v[4:5], s[66:67], 0, v[20:21]
	s_lshl_b32 s19, s70, 5
	v_cndmask_b32_e32 v8, v3, v8, vcc
	v_lshlrev_b32_e32 v73, 2, v8
	v_xor_b32_e32 v8, 4, v3
	v_cmp_lt_i32_e32 vcc, v8, v7
	v_lshlrev_b32_e32 v20, 2, v2
	s_waitcnt lgkmcnt(0)
	v_lshl_add_u64 v[24:25], s[4:5], 0, v[20:21]
	v_cndmask_b32_e32 v8, v3, v8, vcc
	v_lshlrev_b32_e32 v74, 2, v8
	v_xor_b32_e32 v8, 2, v3
	v_cmp_lt_i32_e32 vcc, v8, v7
	v_lshl_add_u64 v[26:27], s[6:7], 0, v[20:21]
	s_add_u32 s6, s66, 0x1a00000
	v_cndmask_b32_e32 v8, v3, v8, vcc
	v_lshlrev_b32_e32 v75, 2, v8
	v_xor_b32_e32 v8, 1, v3
	v_cmp_lt_i32_e32 vcc, v8, v7
	s_mov_b64 s[4:5], 0x9c00000
	s_mov_b64 s[16:17], 0x5c00000
	v_or_b32_e32 v6, 0x200, v2
	s_addc_u32 s7, s67, 0
	v_cndmask_b32_e32 v3, v3, v8, vcc
	v_lshl_add_u64 v[28:29], v[4:5], 0, s[4:5]
	s_mov_b64 s[4:5], 0x1c00000
	s_mov_b32 s22, 0x3727c5ac
	v_lshl_add_u64 v[22:23], v[4:5], 0, s[16:17]
	v_lshlrev_b32_e32 v76, 2, v3
	v_lshl_add_u64 v[30:31], v[4:5], 0, s[4:5]
	s_mov_b64 s[4:5], 0
	s_movk_i32 s20, 0x1fff
	s_movk_i32 s21, 0x6000
	v_mov_b64_e32 v[32:33], s[6:7]
	s_mov_b64 s[6:7], 0x4000
	s_mov_b64 s[16:17], 0x3000
	v_lshlrev_b32_e32 v20, 2, v2
	s_mov_b32 s18, 0x3a800000
	v_lshlrev_b32_e32 v34, 2, v6
	v_mov_b32_e32 v35, v21
	v_mov_b64_e32 v[36:37], s[22:23]
	s_mov_b32 s22, 0x800000
	s_movk_i32 s23, 0x3fff

.LBB0_1365:
	s_or_b64 exec, exec, s[14:15]
	s_cmpk_lg_u32 s70, 0x100
	s_cbranch_scc1 .Lp11_conv
	s_bitcmp1_b32 s2, 3
	s_cbranch_scc1 .LBB0_1371
.Lp11_conv:
	v_lshlrev_b32_e32 v2, 2, v1
	v_lshlrev_b32_e32 v6, 5, v1
	v_lshrrev_b32_e32 v10, 6, v1
	v_and_b32_e32 v2, 0xfc, v2
	v_lshrrev_b32_e32 v11, 1, v1
	v_and_b32_e32 v6, 32, v6
	v_lshl_add_u32 v4, v2, 2, 0
	v_mul_u32_u24_e32 v5, 0x404, v10
	v_lshl_add_u32 v7, v11, 2, 0
	v_mul_u32_u24_e32 v8, 0x404, v6
	s_cmpk_gt_i32 s2, 0x15f
	v_mov_b32_e32 v3, 0
	v_add_u32_e32 v12, v4, v5
	v_add_u32_e32 v13, v7, v8
	v_lshlrev_b32_e32 v4, 2, v2
	v_lshlrev_b32_e32 v2, 1, v6
	s_waitcnt vmcnt(0) lgkmcnt(0)
	s_barrier
	s_cbranch_scc1 .LBB0_1368
	s_add_u32 s4, s66, 0xdc00000
	v_mov_b32_e32 v5, v3
	s_addc_u32 s5, s67, 0
	v_lshl_add_u64 v[6:7], s[8:9], 0, v[4:5]
	s_lshl_b32 s14, s2, 8
	s_lshl_b32 s15, s70, 8
	s_movk_i32 s16, 0x5800
	v_add_u32_e32 v5, 0x2020, v12
	v_add_u32_e32 v8, 0x2028, v12
	v_add_u32_e32 v9, 0x4040, v12
	v_add_u32_e32 v14, 0x4048, v12
	v_add_u32_e32 v15, 0x6060, v12
	v_add_u32_e32 v16, 0x6068, v12
	v_add_u32_e32 v17, 0x8080, v12
	v_add_u32_e32 v18, 0x8088, v12
	v_add_u32_e32 v19, 0xa0a0, v12
	v_add_u32_e32 v20, 0xa0a8, v12
	v_add_u32_e32 v21, 0xc0c0, v12
	v_add_u32_e32 v22, 0xc0c8, v12
	v_add_u32_e32 v23, 0xe0e0, v12
	v_add_u32_e32 v24, 0xe0e8, v12
	s_mov_b32 s17, s2

.LBB0_1368:
	s_cmpk_lg_u32 s70, 0x100
	s_cbranch_scc1 .Lp11_tail
	s_bitcmp1_b32 s2, 3
	s_cbranch_scc0 .Lp11_tail
	s_load_dwordx8 s[4:11], s[0:1], 0xc0
	s_branch .Lp11_ln
